# window tile loop: K/V tiles staged with direct global->LDS loads as well
# speedup vs baseline: 1.0067x; 1.0067x over previous
; DI void nsa_unit(const Ctx& c0, int b, int g, int i, LAS unsigned char* lds) {
;     ...
;         branch_fold(st, g_s2, false, wsf, lane);
; #pragma unroll
;         for (int rg = 0; rg < 16; ++rg) { OACC[rg * 64] = st.o0[rg]; OACC[(16 + rg) * 64] = st.o1[rg]; }
;         __syncthreads();
;     ...
;         const bf16* Kg = (const bf16*)(c.ws + O_KW) + ((size_t)g * T + (size_t)b * SEQ) * 64;
;         const bf16* Vg = (const bf16*)(c.ws + O_VW) + ((size_t)g * T + (size_t)b * SEQ) * 64;
;         ASt st; st.m = NEGB; st.l = 0.f; st.o0 = f32x16{}; st.o1 = f32x16{};
;         const int nlast = i - 8 < 0 ? 0 : i - 8;
;         TileRegs tr = tile_fetch(Kg, Vg, 64 * i, tid);
;         int k = 0;
;         for (int n = i; n >= nlast; --n, ++k) {
;             tile_stage(tr, lds, k & 1, tid);
;             __syncthreads();
;             if (n - 1 >= nlast) tr = tile_fetch(Kg, Vg, 64 * (n - 1), tid);
.LBB0_577:
	s_or_b64 exec, exec, s[12:13]
	s_waitcnt lgkmcnt(0)
	ds_read_b128 v[4:7], v205 offset:32768
	ds_read_b128 v[8:11], v205 offset:32800
	s_add_u32 s3, s0, s94
	s_addc_u32 s12, s1, s95
	s_add_u32 s14, s3, 0x8c00000
	s_waitcnt lgkmcnt(0)
	v_mul_f32_e32 v2, v34, v4
	v_mul_f32_e32 v12, v18, v4
	v_mul_f32_e32 v13, v35, v5
	v_mul_f32_e32 v14, v19, v5
	v_mul_f32_e32 v15, v36, v6
	v_mul_f32_e32 v16, v20, v6
	v_mul_f32_e32 v17, v37, v7
	v_mul_f32_e32 v18, v21, v7
	ds_read_b128 v[4:7], v205 offset:32832
	v_mul_f32_e32 v19, v38, v8
	v_mul_f32_e32 v20, v22, v8
	v_mul_f32_e32 v21, v39, v9
	v_mul_f32_e32 v22, v23, v9
	v_mul_f32_e32 v23, v40, v10
	v_mul_f32_e32 v24, v24, v10
	v_mul_f32_e32 v34, v41, v11
	v_mul_f32_e32 v25, v25, v11
	ds_read_b128 v[8:11], v205 offset:32864
	v_add_u32_e32 v52, s24, v140
	s_waitcnt lgkmcnt(0)
	v_mul_f32_e32 v35, v42, v4
	v_mul_f32_e32 v4, v26, v4
	v_mul_f32_e32 v26, v43, v5
	v_mul_f32_e32 v5, v27, v5
	s_addc_u32 s15, s12, 0
	v_ashrrev_i32_e32 v53, 31, v52
	v_mul_f32_e32 v27, v44, v6
	v_mul_f32_e32 v6, v28, v6
	v_mul_f32_e32 v28, v45, v7
	v_mul_f32_e32 v7, v29, v7
	v_mul_f32_e32 v29, v46, v8
	v_mul_f32_e32 v8, v30, v8
	v_mul_f32_e32 v30, v47, v9
	v_mul_f32_e32 v9, v31, v9
	v_mul_f32_e32 v31, v48, v10
	v_mul_f32_e32 v10, v32, v10
	v_mul_f32_e32 v32, v49, v11
	v_mul_f32_e32 v11, v33, v11
	ds_write2st64_b32 v214, v2, v13 offset0:144 offset1:145
	ds_write2st64_b32 v214, v12, v14 offset0:160 offset1:161
	ds_write2st64_b32 v214, v15, v17 offset0:146 offset1:147
	ds_write2st64_b32 v214, v16, v18 offset0:162 offset1:163
	ds_write2st64_b32 v214, v19, v21 offset0:148 offset1:149
	ds_write2st64_b32 v214, v20, v22 offset0:164 offset1:165
	ds_write2st64_b32 v214, v23, v34 offset0:150 offset1:151
	ds_write2st64_b32 v214, v24, v25 offset0:166 offset1:167
	ds_write2st64_b32 v214, v35, v26 offset0:152 offset1:153
	ds_write2st64_b32 v214, v4, v5 offset0:168 offset1:169
	ds_write2st64_b32 v214, v27, v28 offset0:154 offset1:155
	ds_write2st64_b32 v214, v6, v7 offset0:170 offset1:171
	ds_write2st64_b32 v214, v29, v30 offset0:156 offset1:157
	ds_write2st64_b32 v214, v8, v9 offset0:172 offset1:173
	ds_write2st64_b32 v214, v31, v32 offset0:158 offset1:159
	ds_write2st64_b32 v214, v10, v11 offset0:174 offset1:175
	s_add_u32 s78, s3, 0x9c00000
	s_addc_u32 s79, s12, 0
	s_waitcnt lgkmcnt(0)
	s_barrier
	v_readlane_b32 s83, v250, 4
	s_lshl_b32 m0, s83, 10
	s_lshl_b32 s81, s24, 7
	s_add_u32 s82, s78, s81
	s_addc_u32 s83, s79, 0
	s_add_u32 s80, s14, s81
	s_addc_u32 s81, s15, 0
	global_load_lds_dwordx4 v246, s[80:81]
	s_add_i32 m0, m0, 0x4000
	s_nop 0
	global_load_lds_dwordx4 v247, s[82:83]
	s_cmp_lg_u32 s25, 0
	v_readlane_b32 s90, v250, 15
	s_cselect_b64 s[12:13], -1, 0
	s_cmp_eq_u32 s25, 0
	v_readlane_b32 s91, v250, 16
	s_waitcnt vmcnt(0) lgkmcnt(0)
	s_waitcnt lgkmcnt(0)
	s_barrier
	s_cbranch_scc1 .LBB0_579
	s_add_i32 s81, s24, 0xffffffc0
	s_lshl_b32 s81, s81, 7
	s_add_u32 s82, s78, s81
	s_addc_u32 s83, s79, 0
	s_add_u32 s80, s14, s81
	s_addc_u32 s81, s15, 0
	s_sub_i32 m0, m0, 0x4000
	s_xor_b32 m0, m0, 0x2000
	s_nop 0
	global_load_lds_dwordx4 v246, s[80:81]
	s_add_i32 m0, m0, 0x4000
	s_nop 0
	global_load_lds_dwordx4 v247, s[82:83]

; #define LAS __attribute__((address_space(3)))
; #define LDS_WAIT() asm volatile("s_waitcnt lgkmcnt(0)" ::: "memory")
; #define MFMA32(a, b, c) __builtin_amdgcn_mfma_f32_32x32x16_bf16((a), (b), (c), 0, 0, 0)
; DI s16x4 vtr(const LAS unsigned char* p) { return __builtin_bit_cast(s16x4, __builtin_amdgcn_ds_read_tr16_b64_v4i16((LAS v4i16_t*)p)); }
; template <bool CMP> DI void tile_compute(LAS unsigned char* lds, int buf, const bf16x8 (&q)[4], int lo, int hv, ASt& st, f32x16& imp0, f32x16& imp1, int jt, LAS float* wsf, int lane) {
;     ...
;     float sum = 0.f;
;     const float msub = (!anyPart && dead) ? 1e30f : mnew;
; #pragma unroll
;     for (int rg = 0; rg < 16; ++rg) { p0[rg] = __builtin_amdgcn_exp2f(p0[rg] - msub); p1[rg] = __builtin_amdgcn_exp2f(p1[rg] - msub); sum += p0[rg] + p1[rg]; }
;     st.l = st.l * alpha + sum;
;     if (__builtin_amdgcn_ballot_w64(alpha != 1.f) != 0ull) {
;         if (hi == 0) wsf[r] = alpha;
;         LDS_WAIT();
; #pragma unroll
;         for (int g4 = 0; g4 < 4; ++g4) { const f32x4 f = *(const LAS f32x4*)(wsf + 8 * g4 + 4 * hi);
; #pragma unroll
;             for (int k = 0; k < 4; ++k) { st.o0[4 * g4 + k] *= f[k]; st.o1[4 * g4 + k] *= f[k]; if (CMP) { imp0[4 * g4 + k] *= f[k]; imp1[4 * g4 + k] *= f[k]; } } }
;         LDS_WAIT();
;     }
;     bf16x8 pa[4];
;     pa[0] = pack8(p0[0], p0[1], p0[2], p0[3], p0[4], p0[5], p0[6], p0[7]); pa[1] = pack8(p0[8], p0[9], p0[10], p0[11], p0[12], p0[13], p0[14], p0[15]);
;     pa[2] = pack8(p1[0], p1[1], p1[2], p1[3], p1[4], p1[5], p1[6], p1[7]); pa[3] = pack8(p1[8], p1[9], p1[10], p1[11], p1[12], p1[13], p1[14], p1[15]);
;     const LAS unsigned char* vb = lds + A_VT + buf * 8192 + (4 * hi + ((lane & 15) >> 2)) * 64 + ((lane >> 4) & 1) * 32 + (lane & 3) * 8;
; #pragma unroll
;     for (int s = 0; s < 4; ++s) {
;         const bf16x8 v0 = cat8(vtr(vb + s * 1024), vtr(vb + s * 1024 + 512));
;         const bf16x8 v1 = cat8(vtr(vb + 4096 + s * 1024), vtr(vb + 4096 + s * 1024 + 512));
;         st.o0 = MFMA32(pa[s], v0, st.o0); st.o1 = MFMA32(pa[s], v1, st.o1);
;     }
; DI void nsa_unit(const Ctx& c0, int b, int g, int i, LAS unsigned char* lds) {
;     ...
;         for (int n = i; n >= nlast; --n, ++k) {
;             tile_stage(tr, lds, k & 1, tid);
;             __syncthreads();
;             if (n - 1 >= nlast) tr = tile_fetch(Kg, Vg, 64 * (n - 1), tid);
.LBB0_586:
	v_sub_f32_e32 v2, v20, v78
	v_exp_f32_e32 v20, v2
	v_sub_f32_e32 v2, v36, v78
	v_exp_f32_e32 v36, v2
	v_sub_f32_e32 v21, v21, v78
	v_sub_f32_e32 v37, v37, v78
	v_exp_f32_e32 v21, v21
	v_exp_f32_e32 v37, v37
	v_sub_f32_e32 v22, v22, v78
	v_sub_f32_e32 v38, v38, v78
	v_exp_f32_e32 v22, v22
	v_exp_f32_e32 v38, v38
	v_sub_f32_e32 v23, v23, v78
	v_sub_f32_e32 v39, v39, v78
	v_exp_f32_e32 v23, v23
	v_exp_f32_e32 v39, v39
	v_add_f32_e32 v2, v36, v20
	v_add_f32_e32 v2, 0, v2
	v_add_f32_e32 v54, v37, v21
	v_add_f32_e32 v2, v54, v2
	v_add_f32_e32 v54, v38, v22
	v_add_f32_e32 v2, v54, v2
	v_add_f32_e32 v54, v39, v23
	v_sub_f32_e32 v24, v24, v78
	v_sub_f32_e32 v40, v40, v78
	v_add_f32_e32 v2, v54, v2
	v_exp_f32_e32 v24, v24
	v_exp_f32_e32 v54, v40
	v_sub_f32_e32 v25, v25, v78
	v_exp_f32_e32 v25, v25
	v_sub_f32_e32 v26, v26, v78
	v_add_f32_e32 v40, v54, v24
	v_add_f32_e32 v2, v40, v2
	v_sub_f32_e32 v40, v41, v78
	v_exp_f32_e32 v55, v40
	v_exp_f32_e32 v26, v26
	v_sub_f32_e32 v27, v27, v78
	v_exp_f32_e32 v27, v27
	v_add_f32_e32 v40, v55, v25
	v_add_f32_e32 v2, v40, v2
	v_sub_f32_e32 v40, v42, v78
	v_exp_f32_e32 v56, v40
	v_sub_f32_e32 v28, v28, v78
	v_exp_f32_e32 v28, v28
	v_sub_f32_e32 v29, v29, v78
	v_add_f32_e32 v40, v56, v26
	v_add_f32_e32 v2, v40, v2
	v_sub_f32_e32 v40, v43, v78
	v_exp_f32_e32 v57, v40
	v_exp_f32_e32 v29, v29
	v_sub_f32_e32 v30, v30, v78
	v_exp_f32_e32 v30, v30
	v_add_f32_e32 v40, v57, v27
	v_add_f32_e32 v2, v40, v2
	v_sub_f32_e32 v40, v44, v78
	v_exp_f32_e32 v58, v40
	v_sub_f32_e32 v31, v31, v78
	v_exp_f32_e32 v31, v31
	v_sub_f32_e32 v32, v32, v78
	v_add_f32_e32 v40, v58, v28
	v_add_f32_e32 v2, v40, v2
	v_sub_f32_e32 v40, v45, v78
	v_exp_f32_e32 v59, v40
	v_exp_f32_e32 v32, v32
	v_sub_f32_e32 v33, v33, v78
	v_exp_f32_e32 v33, v33
	v_add_f32_e32 v40, v59, v29
	v_add_f32_e32 v2, v40, v2
	v_sub_f32_e32 v40, v46, v78
	v_exp_f32_e32 v60, v40
	v_sub_f32_e32 v34, v34, v78
	v_exp_f32_e32 v34, v34
	v_sub_f32_e32 v35, v35, v78
	v_add_f32_e32 v40, v60, v30
	v_add_f32_e32 v2, v40, v2
	v_sub_f32_e32 v40, v47, v78
	v_exp_f32_e32 v61, v40
	v_exp_f32_e32 v35, v35
	v_cvt_pk_bf16_f32 v41, v22, v23
	v_cvt_pk_bf16_f32 v42, v24, v25
	v_add_f32_e32 v40, v61, v31
	v_add_f32_e32 v2, v40, v2
	v_sub_f32_e32 v40, v48, v78
	v_exp_f32_e32 v62, v40
	v_cvt_pk_bf16_f32 v43, v26, v27
	v_cvt_pk_bf16_f32 v48, v36, v37
	v_cvt_pk_bf16_f32 v36, v58, v59
	v_add_f32_e32 v40, v62, v32
	v_add_f32_e32 v2, v40, v2
	v_sub_f32_e32 v40, v49, v78
	v_exp_f32_e32 v63, v40
	v_cvt_pk_bf16_f32 v37, v60, v61
	v_cvt_pk_bf16_f32 v44, v28, v29
	v_cvt_pk_bf16_f32 v45, v30, v31
	v_add_f32_e32 v40, v63, v33
	v_add_f32_e32 v2, v40, v2
	v_sub_f32_e32 v40, v50, v78
	v_exp_f32_e32 v64, v40
	v_cvt_pk_bf16_f32 v50, v54, v55
	v_cvt_pk_bf16_f32 v46, v32, v33
	v_cvt_pk_bf16_f32 v47, v34, v35
	v_add_f32_e32 v40, v64, v34
	v_add_f32_e32 v2, v40, v2
	v_sub_f32_e32 v40, v51, v78
	v_exp_f32_e32 v65, v40
	v_cvt_pk_bf16_f32 v51, v56, v57
	ds_read_b64_tr_b16 v[54:55], v215 offset:16384
	ds_read_b64_tr_b16 v[56:57], v215 offset:16896
	ds_read_b64_tr_b16 v[58:59], v215 offset:20480
	ds_read_b64_tr_b16 v[60:61], v215 offset:20992
	v_cvt_pk_bf16_f32 v49, v38, v39
	v_add_f32_e32 v40, v65, v35
	v_add_f32_e32 v2, v40, v2
	v_cvt_pk_bf16_f32 v40, v20, v21
	v_cvt_pk_bf16_f32 v38, v62, v63
	v_cvt_pk_bf16_f32 v39, v64, v65
	s_waitcnt lgkmcnt(0)
	v_mfma_f32_32x32x16_bf16 v[20:35], v[40:43], v[54:57], v[4:19]
	s_add_i32 s3, s25, -8
	s_max_i32 s3, s3, 0
	v_fmac_f32_e32 v2, 0, v53
	s_andn2_b64 vcc, exec, s[12:13]
	v_mfma_f32_32x32x16_bf16 v[4:19], v[40:43], v[58:61], v[4:19]
	ds_read_b64_tr_b16 v[40:41], v215 offset:17408
	ds_read_b64_tr_b16 v[42:43], v215 offset:17920
	ds_read_b64_tr_b16 v[54:55], v215 offset:21504
	ds_read_b64_tr_b16 v[56:57], v215 offset:22016
	s_waitcnt lgkmcnt(0)
	v_mfma_f32_32x32x16_bf16 v[20:35], v[44:47], v[40:43], v[20:35]
	v_mfma_f32_32x32x16_bf16 v[4:19], v[44:47], v[54:57], v[4:19]
	ds_read_b64_tr_b16 v[40:41], v215 offset:18432
	ds_read_b64_tr_b16 v[42:43], v215 offset:18944
	ds_read_b64_tr_b16 v[44:45], v215 offset:22528
	ds_read_b64_tr_b16 v[46:47], v215 offset:23040
	s_waitcnt lgkmcnt(0)
	v_mfma_f32_32x32x16_bf16 v[20:35], v[48:51], v[40:43], v[20:35]
	v_mfma_f32_32x32x16_bf16 v[4:19], v[48:51], v[44:47], v[4:19]
	ds_read_b64_tr_b16 v[40:41], v215 offset:19456
	ds_read_b64_tr_b16 v[42:43], v215 offset:19968
	ds_read_b64_tr_b16 v[44:45], v215 offset:23552
	ds_read_b64_tr_b16 v[46:47], v215 offset:24064
	s_waitcnt lgkmcnt(0)
	v_mfma_f32_32x32x16_bf16 v[20:35], v[36:39], v[40:43], v[20:35]
	v_mfma_f32_32x32x16_bf16 v[4:19], v[36:39], v[44:47], v[4:19]
	s_cbranch_vccnz .LBB0_598
	v_add_u32_e32 v36, 0xffffff80, v52
	v_ashrrev_i32_e32 v37, 31, v36
	s_add_u32 s12, s0, s21
	v_lshlrev_b64 v[36:37], 7, v[36:37]
	s_addc_u32 s13, s1, s22
	v_or_b32_e32 v36, v36, v136
	v_lshl_add_u64 v[76:77], s[12:13], 0, v[36:37]
	s_add_i32 s98, s24, 0xffffff80
	s_lshl_b32 s98, s98, 7
	s_add_u32 s98, s12, s98
	s_addc_u32 s99, s13, 0
	s_mov_b64 s[12:13], 0
	s_movk_i32 s84, 0x2000
.LBB0_588:
	s_and_b32 s14, s84, 0x2000
	s_add_i32 s25, s25, -1
	s_add_i32 s88, s14, 0
	s_cmp_le_i32 s25, s3
	s_cselect_b64 s[82:83], -1, 0
	s_and_b64 vcc, exec, s[82:83]
	s_waitcnt vmcnt(0) lgkmcnt(0)
	s_barrier
	s_cbranch_vccnz .LBB0_590
	s_add_u32 s78, s98, s12
	s_addc_u32 s79, s99, s13
	s_add_u32 s80, s78, 0x9c00000
	s_addc_u32 s81, s79, 0
	s_add_u32 s78, s78, 0x8c00000
	s_addc_u32 s79, s79, 0
	s_sub_i32 m0, m0, 0x4000
	s_xor_b32 m0, m0, 0x2000
	s_nop 0
	global_load_lds_dwordx4 v246, s[78:79]
	s_add_i32 m0, m0, 0x4000
	s_nop 0
	global_load_lds_dwordx4 v247, s[80:81]

; DI void nsa_unit(const Ctx& c0, int b, int g, int i, LAS unsigned char* lds) {
;     ...
;         branch_fold(st, g_s2, false, wsf, lane);
; #pragma unroll
;         for (int rg = 0; rg < 16; ++rg) { OACC[rg * 64] = st.o0[rg]; OACC[(16 + rg) * 64] = st.o1[rg]; }
;         __syncthreads();
;     ...
;         const bf16* Kg = (const bf16*)(c.ws + O_KW) + ((size_t)g * T + (size_t)b * SEQ) * 64;
;         const bf16* Vg = (const bf16*)(c.ws + O_VW) + ((size_t)g * T + (size_t)b * SEQ) * 64;
;         ASt st; st.m = NEGB; st.l = 0.f; st.o0 = f32x16{}; st.o1 = f32x16{};
;         const int nlast = i - 8 < 0 ? 0 : i - 8;
;         TileRegs tr = tile_fetch(Kg, Vg, 64 * i, tid);
;         int k = 0;
;         for (int n = i; n >= nlast; --n, ++k) {
;             tile_stage(tr, lds, k & 1, tid);
;             __syncthreads();
;             if (n - 1 >= nlast) tr = tile_fetch(Kg, Vg, 64 * (n - 1), tid);
.LBB0_1190:
	s_or_b64 exec, exec, s[14:15]
	s_waitcnt lgkmcnt(0)
	ds_read_b128 v[4:7], v192 offset:32768
	ds_read_b128 v[8:11], v192 offset:32800
	s_add_u32 s6, s0, s2
	s_addc_u32 s14, s1, s3
	s_add_u32 s16, s6, 0x8c00000
	s_waitcnt lgkmcnt(0)
	v_mul_f32_e32 v2, v34, v4
	v_mul_f32_e32 v12, v18, v4
	v_mul_f32_e32 v13, v35, v5
	v_mul_f32_e32 v14, v19, v5
	v_mul_f32_e32 v15, v36, v6
	v_mul_f32_e32 v16, v20, v6
	v_mul_f32_e32 v17, v37, v7
	v_mul_f32_e32 v18, v21, v7
	ds_read_b128 v[4:7], v192 offset:32832
	v_mul_f32_e32 v19, v38, v8
	v_mul_f32_e32 v20, v22, v8
	v_mul_f32_e32 v21, v39, v9
	v_mul_f32_e32 v22, v23, v9
	v_mul_f32_e32 v23, v40, v10
	v_mul_f32_e32 v24, v24, v10
	v_mul_f32_e32 v34, v41, v11
	v_mul_f32_e32 v25, v25, v11
	ds_read_b128 v[8:11], v192 offset:32864
	v_add_u32_e32 v52, s26, v140
	s_waitcnt lgkmcnt(0)
	v_mul_f32_e32 v35, v42, v4
	v_mul_f32_e32 v4, v26, v4
	v_mul_f32_e32 v26, v43, v5
	v_mul_f32_e32 v5, v27, v5
	s_addc_u32 s17, s14, 0
	v_ashrrev_i32_e32 v53, 31, v52
	v_mul_f32_e32 v27, v44, v6
	v_mul_f32_e32 v6, v28, v6
	v_mul_f32_e32 v28, v45, v7
	v_mul_f32_e32 v7, v29, v7
	v_mul_f32_e32 v29, v46, v8
	v_mul_f32_e32 v8, v30, v8
	v_mul_f32_e32 v30, v47, v9
	v_mul_f32_e32 v9, v31, v9
	v_mul_f32_e32 v31, v48, v10
	v_mul_f32_e32 v10, v32, v10
	v_mul_f32_e32 v32, v49, v11
	v_mul_f32_e32 v11, v33, v11
	ds_write2st64_b32 v190, v2, v13 offset0:144 offset1:145
	ds_write2st64_b32 v190, v12, v14 offset0:160 offset1:161
	ds_write2st64_b32 v190, v15, v17 offset0:146 offset1:147
	ds_write2st64_b32 v190, v16, v18 offset0:162 offset1:163
	ds_write2st64_b32 v190, v19, v21 offset0:148 offset1:149
	ds_write2st64_b32 v190, v20, v22 offset0:164 offset1:165
	ds_write2st64_b32 v190, v23, v34 offset0:150 offset1:151
	ds_write2st64_b32 v190, v24, v25 offset0:166 offset1:167
	ds_write2st64_b32 v190, v35, v26 offset0:152 offset1:153
	ds_write2st64_b32 v190, v4, v5 offset0:168 offset1:169
	ds_write2st64_b32 v190, v27, v28 offset0:154 offset1:155
	ds_write2st64_b32 v190, v6, v7 offset0:170 offset1:171
	ds_write2st64_b32 v190, v29, v30 offset0:156 offset1:157
	ds_write2st64_b32 v190, v8, v9 offset0:172 offset1:173
	ds_write2st64_b32 v190, v31, v32 offset0:158 offset1:159
	ds_write2st64_b32 v190, v10, v11 offset0:174 offset1:175
	s_add_u32 s80, s6, 0x9c00000
	s_addc_u32 s81, s14, 0
	s_waitcnt lgkmcnt(0)
	s_barrier
	v_readlane_b32 s87, v250, 4
	s_lshl_b32 m0, s87, 10
	s_lshl_b32 s83, s26, 7
	s_add_u32 s86, s80, s83
	s_addc_u32 s87, s81, 0
	s_add_u32 s82, s16, s83
	s_addc_u32 s83, s17, 0
	global_load_lds_dwordx4 v246, s[82:83]
	s_add_i32 m0, m0, 0x4000
	s_nop 0
	global_load_lds_dwordx4 v247, s[86:87]
	s_cmp_lg_u32 s27, 0
	v_readlane_b32 s90, v250, 15
	s_cselect_b64 s[14:15], -1, 0
	s_cmp_eq_u32 s27, 0
	v_readlane_b32 s91, v250, 16
	s_waitcnt vmcnt(0) lgkmcnt(0)
	s_waitcnt lgkmcnt(0)
	s_barrier
	s_cbranch_scc1 .LBB0_1192
	s_add_i32 s83, s26, 0xffffffc0
	s_lshl_b32 s83, s83, 7
	s_add_u32 s86, s80, s83
	s_addc_u32 s87, s81, 0
	s_add_u32 s82, s16, s83
	s_addc_u32 s83, s17, 0
	s_sub_i32 m0, m0, 0x4000
	s_xor_b32 m0, m0, 0x2000
	s_nop 0
	global_load_lds_dwordx4 v246, s[82:83]
	s_add_i32 m0, m0, 0x4000
	s_nop 0
	global_load_lds_dwordx4 v247, s[86:87]

; #define LAS __attribute__((address_space(3)))
; #define LDS_WAIT() asm volatile("s_waitcnt lgkmcnt(0)" ::: "memory")
; #define MFMA32(a, b, c) __builtin_amdgcn_mfma_f32_32x32x16_bf16((a), (b), (c), 0, 0, 0)
; DI s16x4 vtr(const LAS unsigned char* p) { return __builtin_bit_cast(s16x4, __builtin_amdgcn_ds_read_tr16_b64_v4i16((LAS v4i16_t*)p)); }
; template <bool CMP> DI void tile_compute(LAS unsigned char* lds, int buf, const bf16x8 (&q)[4], int lo, int hv, ASt& st, f32x16& imp0, f32x16& imp1, int jt, LAS float* wsf, int lane) {
;     ...
;     float sum = 0.f;
;     const float msub = (!anyPart && dead) ? 1e30f : mnew;
; #pragma unroll
;     for (int rg = 0; rg < 16; ++rg) { p0[rg] = __builtin_amdgcn_exp2f(p0[rg] - msub); p1[rg] = __builtin_amdgcn_exp2f(p1[rg] - msub); sum += p0[rg] + p1[rg]; }
;     st.l = st.l * alpha + sum;
;     if (__builtin_amdgcn_ballot_w64(alpha != 1.f) != 0ull) {
;         if (hi == 0) wsf[r] = alpha;
;         LDS_WAIT();
; #pragma unroll
;         for (int g4 = 0; g4 < 4; ++g4) { const f32x4 f = *(const LAS f32x4*)(wsf + 8 * g4 + 4 * hi);
; #pragma unroll
;             for (int k = 0; k < 4; ++k) { st.o0[4 * g4 + k] *= f[k]; st.o1[4 * g4 + k] *= f[k]; if (CMP) { imp0[4 * g4 + k] *= f[k]; imp1[4 * g4 + k] *= f[k]; } } }
;         LDS_WAIT();
;     }
;     bf16x8 pa[4];
;     pa[0] = pack8(p0[0], p0[1], p0[2], p0[3], p0[4], p0[5], p0[6], p0[7]); pa[1] = pack8(p0[8], p0[9], p0[10], p0[11], p0[12], p0[13], p0[14], p0[15]);
;     pa[2] = pack8(p1[0], p1[1], p1[2], p1[3], p1[4], p1[5], p1[6], p1[7]); pa[3] = pack8(p1[8], p1[9], p1[10], p1[11], p1[12], p1[13], p1[14], p1[15]);
;     const LAS unsigned char* vb = lds + A_VT + buf * 8192 + (4 * hi + ((lane & 15) >> 2)) * 64 + ((lane >> 4) & 1) * 32 + (lane & 3) * 8;
; #pragma unroll
;     for (int s = 0; s < 4; ++s) {
;         const bf16x8 v0 = cat8(vtr(vb + s * 1024), vtr(vb + s * 1024 + 512));
;         const bf16x8 v1 = cat8(vtr(vb + 4096 + s * 1024), vtr(vb + 4096 + s * 1024 + 512));
;         st.o0 = MFMA32(pa[s], v0, st.o0); st.o1 = MFMA32(pa[s], v1, st.o1);
;     }
; DI void nsa_unit(const Ctx& c0, int b, int g, int i, LAS unsigned char* lds) {
;     ...
;         for (int n = i; n >= nlast; --n, ++k) {
;             tile_stage(tr, lds, k & 1, tid);
;             __syncthreads();
;             if (n - 1 >= nlast) tr = tile_fetch(Kg, Vg, 64 * (n - 1), tid);
.LBB0_1199:
	v_sub_f32_e32 v2, v20, v78
	v_exp_f32_e32 v20, v2
	v_sub_f32_e32 v2, v36, v78
	v_exp_f32_e32 v36, v2
	v_sub_f32_e32 v21, v21, v78
	v_sub_f32_e32 v37, v37, v78
	v_exp_f32_e32 v21, v21
	v_exp_f32_e32 v37, v37
	v_sub_f32_e32 v22, v22, v78
	v_sub_f32_e32 v38, v38, v78
	v_exp_f32_e32 v22, v22
	v_exp_f32_e32 v38, v38
	v_sub_f32_e32 v23, v23, v78
	v_sub_f32_e32 v39, v39, v78
	v_exp_f32_e32 v23, v23
	v_exp_f32_e32 v39, v39
	v_add_f32_e32 v2, v36, v20
	v_add_f32_e32 v2, 0, v2
	v_add_f32_e32 v54, v37, v21
	v_add_f32_e32 v2, v54, v2
	v_add_f32_e32 v54, v38, v22
	v_add_f32_e32 v2, v54, v2
	v_add_f32_e32 v54, v39, v23
	v_sub_f32_e32 v24, v24, v78
	v_sub_f32_e32 v40, v40, v78
	v_add_f32_e32 v2, v54, v2
	v_exp_f32_e32 v24, v24
	v_exp_f32_e32 v54, v40
	v_sub_f32_e32 v25, v25, v78
	v_exp_f32_e32 v25, v25
	v_sub_f32_e32 v26, v26, v78
	v_add_f32_e32 v40, v54, v24
	v_add_f32_e32 v2, v40, v2
	v_sub_f32_e32 v40, v41, v78
	v_exp_f32_e32 v55, v40
	v_exp_f32_e32 v26, v26
	v_sub_f32_e32 v27, v27, v78
	v_exp_f32_e32 v27, v27
	v_add_f32_e32 v40, v55, v25
	v_add_f32_e32 v2, v40, v2
	v_sub_f32_e32 v40, v42, v78
	v_exp_f32_e32 v56, v40
	v_sub_f32_e32 v28, v28, v78
	v_exp_f32_e32 v28, v28
	v_sub_f32_e32 v29, v29, v78
	v_add_f32_e32 v40, v56, v26
	v_add_f32_e32 v2, v40, v2
	v_sub_f32_e32 v40, v43, v78
	v_exp_f32_e32 v57, v40
	v_exp_f32_e32 v29, v29
	v_sub_f32_e32 v30, v30, v78
	v_exp_f32_e32 v30, v30
	v_add_f32_e32 v40, v57, v27
	v_add_f32_e32 v2, v40, v2
	v_sub_f32_e32 v40, v44, v78
	v_exp_f32_e32 v58, v40
	v_sub_f32_e32 v31, v31, v78
	v_exp_f32_e32 v31, v31
	v_sub_f32_e32 v32, v32, v78
	v_add_f32_e32 v40, v58, v28
	v_add_f32_e32 v2, v40, v2
	v_sub_f32_e32 v40, v45, v78
	v_exp_f32_e32 v59, v40
	v_exp_f32_e32 v32, v32
	v_sub_f32_e32 v33, v33, v78
	v_exp_f32_e32 v33, v33
	v_add_f32_e32 v40, v59, v29
	v_add_f32_e32 v2, v40, v2
	v_sub_f32_e32 v40, v46, v78
	v_exp_f32_e32 v60, v40
	v_sub_f32_e32 v34, v34, v78
	v_exp_f32_e32 v34, v34
	v_sub_f32_e32 v35, v35, v78
	v_add_f32_e32 v40, v60, v30
	v_add_f32_e32 v2, v40, v2
	v_sub_f32_e32 v40, v47, v78
	v_exp_f32_e32 v61, v40
	v_exp_f32_e32 v35, v35
	v_cvt_pk_bf16_f32 v41, v22, v23
	v_cvt_pk_bf16_f32 v42, v24, v25
	v_add_f32_e32 v40, v61, v31
	v_add_f32_e32 v2, v40, v2
	v_sub_f32_e32 v40, v48, v78
	v_exp_f32_e32 v62, v40
	v_cvt_pk_bf16_f32 v43, v26, v27
	v_cvt_pk_bf16_f32 v48, v36, v37
	v_cvt_pk_bf16_f32 v36, v58, v59
	v_add_f32_e32 v40, v62, v32
	v_add_f32_e32 v2, v40, v2
	v_sub_f32_e32 v40, v49, v78
	v_exp_f32_e32 v63, v40
	v_cvt_pk_bf16_f32 v37, v60, v61
	v_cvt_pk_bf16_f32 v44, v28, v29
	v_cvt_pk_bf16_f32 v45, v30, v31
	v_add_f32_e32 v40, v63, v33
	v_add_f32_e32 v2, v40, v2
	v_sub_f32_e32 v40, v50, v78
	v_exp_f32_e32 v64, v40
	v_cvt_pk_bf16_f32 v50, v54, v55
	v_cvt_pk_bf16_f32 v46, v32, v33
	v_cvt_pk_bf16_f32 v47, v34, v35
	v_add_f32_e32 v40, v64, v34
	v_add_f32_e32 v2, v40, v2
	v_sub_f32_e32 v40, v51, v78
	v_exp_f32_e32 v65, v40
	v_cvt_pk_bf16_f32 v51, v56, v57
	ds_read_b64_tr_b16 v[54:55], v210 offset:16384
	ds_read_b64_tr_b16 v[56:57], v210 offset:16896
	ds_read_b64_tr_b16 v[58:59], v210 offset:20480
	ds_read_b64_tr_b16 v[60:61], v210 offset:20992
	v_cvt_pk_bf16_f32 v49, v38, v39
	v_add_f32_e32 v40, v65, v35
	v_add_f32_e32 v2, v40, v2
	v_cvt_pk_bf16_f32 v40, v20, v21
	v_cvt_pk_bf16_f32 v38, v62, v63
	v_cvt_pk_bf16_f32 v39, v64, v65
	s_waitcnt lgkmcnt(0)
	v_mfma_f32_32x32x16_bf16 v[20:35], v[40:43], v[54:57], v[4:19]
	s_add_i32 s6, s27, -8
	s_max_i32 s6, s6, 0
	v_fmac_f32_e32 v2, 0, v53
	s_andn2_b64 vcc, exec, s[14:15]
	v_mfma_f32_32x32x16_bf16 v[4:19], v[40:43], v[58:61], v[4:19]
	ds_read_b64_tr_b16 v[40:41], v210 offset:17408
	ds_read_b64_tr_b16 v[42:43], v210 offset:17920
	ds_read_b64_tr_b16 v[54:55], v210 offset:21504
	ds_read_b64_tr_b16 v[56:57], v210 offset:22016
	s_waitcnt lgkmcnt(0)
	v_mfma_f32_32x32x16_bf16 v[20:35], v[44:47], v[40:43], v[20:35]
	v_mfma_f32_32x32x16_bf16 v[4:19], v[44:47], v[54:57], v[4:19]
	ds_read_b64_tr_b16 v[40:41], v210 offset:18432
	ds_read_b64_tr_b16 v[42:43], v210 offset:18944
	ds_read_b64_tr_b16 v[44:45], v210 offset:22528
	ds_read_b64_tr_b16 v[46:47], v210 offset:23040
	s_waitcnt lgkmcnt(0)
	v_mfma_f32_32x32x16_bf16 v[20:35], v[48:51], v[40:43], v[20:35]
	v_mfma_f32_32x32x16_bf16 v[4:19], v[48:51], v[44:47], v[4:19]
	ds_read_b64_tr_b16 v[40:41], v210 offset:19456
	ds_read_b64_tr_b16 v[42:43], v210 offset:19968
	ds_read_b64_tr_b16 v[44:45], v210 offset:23552
	ds_read_b64_tr_b16 v[46:47], v210 offset:24064
	s_waitcnt lgkmcnt(0)
	v_mfma_f32_32x32x16_bf16 v[20:35], v[36:39], v[40:43], v[20:35]
	v_mfma_f32_32x32x16_bf16 v[4:19], v[36:39], v[44:47], v[4:19]
	s_cbranch_vccnz .LBB0_1211
	v_add_u32_e32 v36, 0xffffff80, v52
	v_ashrrev_i32_e32 v37, 31, v36
	s_add_u32 s14, s0, s23
	v_lshlrev_b64 v[36:37], 7, v[36:37]
	s_addc_u32 s15, s1, s24
	v_or_b32_e32 v36, v36, v136
	v_lshl_add_u64 v[76:77], s[14:15], 0, v[36:37]
	s_add_i32 s98, s26, 0xffffff80
	s_lshl_b32 s98, s98, 7
	s_add_u32 s98, s14, s98
	s_addc_u32 s99, s15, 0
	s_mov_b64 s[14:15], 0
	s_movk_i32 s88, 0x2000
.LBB0_1201:
	s_and_b32 s16, s88, 0x2000
	s_add_i32 s27, s27, -1
	s_add_i32 s28, s16, 0
	s_cmp_le_i32 s27, s6
	s_cselect_b64 s[86:87], -1, 0
	s_and_b64 vcc, exec, s[86:87]
	s_waitcnt vmcnt(0) lgkmcnt(0)
	s_barrier
	s_cbranch_vccnz .LBB0_1203
	s_add_u32 s80, s98, s14
	s_addc_u32 s81, s99, s15
	s_add_u32 s82, s80, 0x9c00000
	s_addc_u32 s83, s81, 0
	s_add_u32 s80, s80, 0x8c00000
	s_addc_u32 s81, s81, 0
	s_sub_i32 m0, m0, 0x4000
	s_xor_b32 m0, m0, 0x2000
	s_nop 0
	global_load_lds_dwordx4 v246, s[80:81]
	s_add_i32 m0, m0, 0x4000
	s_nop 0
	global_load_lds_dwordx4 v247, s[82:83]
